# combo13 + E40: in each in-proj tile epilogue every CU pulls its 1/8 share of the next tile's weight column panel through the L2 (one LDS-DMA dword load per wave into spare LDS, data unused) so the mai
# speedup vs baseline: 1.0214x; 1.0078x over previous
.Ldp1_skip:
	s_waitcnt vmcnt(0)
	v_readlane_b32 s0, v251, 22
	v_mov_b32_e32 v5, v167
	v_readlane_b32 s1, v251, 23
	s_andn2_b64 vcc, exec, s[0:1]
	v_readfirstlane_b32 s10, v5
	s_cbranch_vccnz .LBB0_419
	v_readfirstlane_b32 s3, v5
	s_lshr_b32 s3, s3, 6
	s_lshl_b32 s3, s3, 8
	s_add_i32 s3, s3, 0x20400
	v_lshlrev_b32_e32 v0, 4, v5
	s_waitcnt lgkmcnt(0)
	v_add_u32_e32 v1, 0x2000, v0
	v_ashrrev_i32_e32 v2, 31, v1
	v_lshrrev_b32_e32 v2, 22, v2
	v_add_u32_e32 v2, v1, v2
	v_ashrrev_i32_e32 v4, 10, v2
	v_mul_i32_i24_e32 v2, 0x400, v4
	v_sub_u32_e32 v1, v1, v2
	v_lshrrev_b32_e32 v2, 4, v1
	v_bitop3_b32 v1, v2, v1, 32 bitop3:0x6c
	v_ashrrev_i32_e32 v2, 31, v1
	v_readlane_b32 s0, v254, 62
	v_lshrrev_b32_e32 v2, 26, v2
	v_readlane_b32 s1, v254, 63
	v_add_u32_e32 v2, v1, v2
	v_lshlrev_b32_e32 v3, 3, v4
	s_ashr_i32 s1, s0, 31
	v_ashrrev_i32_e32 v6, 6, v2
	v_and_b32_e32 v3, -16, v3
	s_lshl_b64 s[0:1], s[0:1], 24
	v_readlane_b32 s8, v251, 12
	v_add_u32_e32 v3, v6, v3
	s_add_u32 s14, s8, s0
	v_and_b32_e32 v7, 3, v6
	s_mov_b32 s0, 0x1fffe0
	s_waitcnt vmcnt(0)
	v_lshrrev_b32_e32 v8, 2, v3
	v_lshlrev_b32_e32 v9, 1, v3
	v_and_b32_e32 v2, 0xc0, v2
	v_and_or_b32 v7, v3, s0, v7
	v_and_b32_e32 v8, 4, v8
	v_and_b32_e32 v9, 24, v9
	v_sub_u32_e32 v1, v1, v2
	v_mov_b32_e32 v12, 1
	v_or3_b32 v8, v7, v8, v9
	v_lshlrev_b32_e32 v7, 5, v4
	v_ashrrev_i16_sdwa v1, v12, sext(v1) dst_sel:DWORD dst_unused:UNUSED_PAD src0_sel:DWORD src1_sel:BYTE_0
	v_and_b32_e32 v9, 32, v7
	v_bfe_i32 v7, v1, 0, 16
	v_add_lshl_u32 v1, v9, v7, 1
	v_lshl_add_u32 v148, v8, 11, v1
	v_lshl_add_u32 v150, v3, 11, v1
	v_bfe_i32 v1, v5, 27, 1
	v_lshrrev_b32_e32 v1, 22, v1
	v_add_u32_e32 v1, v0, v1
	v_and_b32_e32 v1, 0xfffffc00, v1
	v_sub_u32_e32 v0, v0, v1
	v_lshrrev_b32_e32 v1, 4, v0
	v_ashrrev_i32_e32 v2, 31, v5
	v_bitop3_b32 v0, v1, v0, 32 bitop3:0x6c
	v_lshrrev_b32_e32 v2, 26, v2
	v_ashrrev_i32_e32 v1, 31, v0
	v_add_u32_e32 v2, v5, v2
	v_lshrrev_b32_e32 v1, 26, v1
	v_ashrrev_i32_e32 v9, 6, v2
	v_add_u32_e32 v1, v0, v1
	v_lshlrev_b32_e32 v2, 3, v9
	v_ashrrev_i32_e32 v8, 6, v1
	v_and_b32_e32 v2, -16, v2
	v_add_u32_e32 v2, v8, v2
	v_and_b32_e32 v3, 3, v8
	v_lshrrev_b32_e32 v10, 2, v2
	v_lshlrev_b32_e32 v11, 1, v2
	v_and_b32_e32 v1, 0xc0, v1
	v_readlane_b32 s9, v251, 13
	v_and_or_b32 v3, v2, s0, v3
	v_and_b32_e32 v10, 4, v10
	v_and_b32_e32 v11, 24, v11
	v_sub_u32_e32 v0, v0, v1
	s_addc_u32 s15, s9, s1
	s_ashr_i32 s11, s10, 6
	v_or3_b32 v3, v3, v10, v11
	v_lshlrev_b32_e32 v10, 5, v9
	v_ashrrev_i16_sdwa v0, v12, sext(v0) dst_sel:DWORD dst_unused:UNUSED_PAD src0_sel:DWORD src1_sel:BYTE_0
	s_lshl_b32 s16, s11, 10
	v_and_b32_e32 v11, 32, v10
	v_bfe_i32 v10, v0, 0, 16
	v_add_lshl_u32 v0, v11, v10, 1
	s_add_i32 s17, s16, 16
	v_readlane_b32 s0, v253, 56
	v_lshl_add_u32 v152, v3, 11, v0
	s_add_i32 m0, s17, 0x10000
	v_readlane_b32 s1, v253, 57
	s_ashr_i32 s12, s10, 8
	v_lshl_add_u32 v154, v2, 11, v0
	v_mov_b32_e32 v155, v157
	v_mov_b32_e32 v151, v157
	s_nop 0
	global_load_lds_dwordx4 v152, s[0:1]
	s_add_i32 m0, s17, 0x12000
	s_nop 0
	global_load_lds_dwordx4 v148, s[0:1]
	v_readlane_b32 s0, v253, 54
	s_add_i32 m0, s17, 0x14000
	v_readlane_b32 s1, v253, 55
	s_nop 4
	global_load_lds_dwordx4 v152, s[0:1]
	s_add_i32 m0, s17, 0x16000
	s_nop 0
	global_load_lds_dwordx4 v148, s[0:1]
	v_readlane_b32 s0, v253, 51
	v_readlane_b32 s1, v253, 52
	s_add_u32 s8, s14, s0
	s_addc_u32 s9, s15, s1
	s_add_i32 s18, s17, 0x2000
	s_mov_b32 m0, s17
	s_add_u32 s0, s8, 0x40000
	global_load_lds_dwordx4 v154, s[8:9]
	s_mov_b32 m0, s18
	s_addc_u32 s1, s9, 0
	s_add_i32 s19, s17, 0x4000
	global_load_lds_dwordx4 v150, s[8:9]
	s_mov_b32 m0, s19
	s_add_i32 s20, s17, 0x6000
	global_load_lds_dwordx4 v154, s[0:1]
	s_mov_b32 m0, s20
	s_cmp_eq_u32 s12, 1
	global_load_lds_dwordx4 v150, s[0:1]
	v_lshl_add_u64 v[0:1], s[8:9], 0, v[154:155]
	s_cselect_b64 s[0:1], -1, 0
	s_cmp_lg_u32 s12, 1
	v_lshl_add_u64 v[2:3], s[8:9], 0, v[150:151]
	s_cbranch_scc1 .LBB0_271
	s_barrier

.LBB0_283:
	s_and_b32 s8, s25, -16
	s_cmp_lg_u32 s8, 16
	s_mov_b64 s[8:9], -1
	s_cbranch_scc0 .LBB0_393
	s_cmp_gt_i32 s25, 59
	s_cbranch_scc0 .LBB0_286
	v_ashrrev_i32_e32 v179, 31, v178
	v_lshlrev_b64 v[128:129], 10, v[178:179]
	v_lshl_add_u64 v[136:137], v[170:171], 0, v[128:129]
	global_load_dwordx4 v[128:131], v[176:177], off offset:16
	global_load_dwordx4 v[132:135], v[176:177], off
	s_movk_i32 s8, 0x4000
	v_add_co_u32_e32 v142, vcc, s8, v136
	s_mov_b32 s8, 0x8000
	s_nop 0
	v_addc_co_u32_e32 v143, vcc, 0, v137, vcc
	s_waitcnt vmcnt(0)
	v_lshrrev_b32_e32 v244, 4, v167
	v_and_b32_e32 v245, 15, v167
	v_lshlrev_b32_e32 v244, 11, v244
	v_lshl_or_b32 v244, v245, 7, v244
	v_mov_b32_e32 v245, s44
	v_and_b32_e32 v245, 7, v245
	v_lshl_add_u32 v244, v245, 16, v244
	s_mov_b32 m0, s3
	s_nop 0
	global_load_lds_dword v244, s[48:49]
	v_pk_add_f32 v[140:141], v[126:127], v[134:135]
	v_pk_add_f32 v[138:139], v[124:125], v[132:133]
	global_store_dwordx4 v[136:137], v[138:141], off
	s_nop 1
	v_pk_add_f32 v[140:141], v[122:123], v[130:131]
	v_pk_add_f32 v[138:139], v[120:121], v[128:129]
	global_store_dwordx4 v[136:137], v[138:141], off offset:16
	s_nop 1
	v_pk_add_f32 v[140:141], v[118:119], v[134:135]
	v_pk_add_f32 v[138:139], v[116:117], v[132:133]
	global_store_dwordx4 v[142:143], v[138:141], off
	s_nop 1
	v_pk_add_f32 v[140:141], v[114:115], v[130:131]
	v_pk_add_f32 v[138:139], v[112:113], v[128:129]
	global_store_dwordx4 v[142:143], v[138:141], off offset:16
	v_add_co_u32_e32 v142, vcc, s8, v136
	s_nop 0
	v_pk_add_f32 v[140:141], v[110:111], v[134:135]
	v_pk_add_f32 v[138:139], v[108:109], v[132:133]
	v_addc_co_u32_e32 v143, vcc, 0, v137, vcc
	global_store_dwordx4 v[142:143], v[138:141], off
	s_mov_b32 s8, 0xc000
	s_nop 0
	v_pk_add_f32 v[140:141], v[106:107], v[130:131]
	v_pk_add_f32 v[138:139], v[104:105], v[128:129]
	global_store_dwordx4 v[142:143], v[138:141], off offset:16
	v_add_co_u32_e32 v142, vcc, s8, v136
	s_nop 0
	v_pk_add_f32 v[140:141], v[102:103], v[134:135]
	v_pk_add_f32 v[138:139], v[100:101], v[132:133]
	v_addc_co_u32_e32 v143, vcc, 0, v137, vcc
	global_store_dwordx4 v[142:143], v[138:141], off
	s_mov_b32 s8, 0x20000
	s_nop 0
	v_pk_add_f32 v[140:141], v[98:99], v[130:131]
	v_pk_add_f32 v[138:139], v[96:97], v[128:129]
	global_store_dwordx4 v[142:143], v[138:141], off offset:16
	v_add_co_u32_e32 v142, vcc, s8, v136
	s_nop 0
	v_pk_add_f32 v[140:141], v[94:95], v[134:135]
	v_pk_add_f32 v[138:139], v[92:93], v[132:133]
	v_addc_co_u32_e32 v143, vcc, 0, v137, vcc
	global_store_dwordx4 v[142:143], v[138:141], off
	s_mov_b32 s8, 0x24000
	s_nop 0
	v_pk_add_f32 v[140:141], v[90:91], v[130:131]
	v_pk_add_f32 v[138:139], v[88:89], v[128:129]
	global_store_dwordx4 v[142:143], v[138:141], off offset:16
	v_add_co_u32_e32 v142, vcc, s8, v136
	s_nop 0
	v_pk_add_f32 v[140:141], v[86:87], v[134:135]
	v_pk_add_f32 v[138:139], v[84:85], v[132:133]
	v_addc_co_u32_e32 v143, vcc, 0, v137, vcc
	global_store_dwordx4 v[142:143], v[138:141], off
	s_mov_b32 s8, 0x28000
	s_nop 0
	v_pk_add_f32 v[140:141], v[82:83], v[130:131]
	v_pk_add_f32 v[138:139], v[80:81], v[128:129]
	global_store_dwordx4 v[142:143], v[138:141], off offset:16
	v_add_co_u32_e32 v142, vcc, s8, v136
	s_nop 0
	v_pk_add_f32 v[140:141], v[78:79], v[134:135]
	v_addc_co_u32_e32 v143, vcc, 0, v137, vcc
	v_pk_add_f32 v[138:139], v[76:77], v[132:133]
	v_add_co_u32_e32 v136, vcc, 0x2c000, v136
	global_store_dwordx4 v[142:143], v[138:141], off
	v_pk_add_f32 v[134:135], v[62:63], v[134:135]
	v_pk_add_f32 v[132:133], v[60:61], v[132:133]
	v_pk_add_f32 v[140:141], v[74:75], v[130:131]
	v_pk_add_f32 v[138:139], v[72:73], v[128:129]
	v_addc_co_u32_e32 v137, vcc, 0, v137, vcc
	v_pk_add_f32 v[130:131], v[58:59], v[130:131]
	v_pk_add_f32 v[128:129], v[56:57], v[128:129]
	global_store_dwordx4 v[142:143], v[138:141], off offset:16
	global_store_dwordx4 v[136:137], v[132:135], off
	global_store_dwordx4 v[136:137], v[128:131], off offset:16
	s_mov_b64 s[8:9], 0

.LBB0_343:
	v_lshl_add_u64 v[138:139], v[138:139], 0, s[52:53]
	v_cvt_pk_bf16_f32 v128, v140, v142
	v_cvt_pk_bf16_f32 v129, v144, v147
	v_cvt_pk_bf16_f32 v130, v141, v143
	v_cvt_pk_bf16_f32 v131, v145, v146
	global_store_dwordx4 v[138:139], v[128:131], off
	s_cmp_gt_i32 s12, 1
	s_mov_b64 s[8:9], -1
	s_waitcnt vmcnt(8)
	v_lshrrev_b32_e32 v244, 4, v167
	v_and_b32_e32 v245, 15, v167
	v_lshlrev_b32_e32 v244, 11, v244
	v_lshl_or_b32 v244, v245, 7, v244
	v_mov_b32_e32 v245, s44
	v_and_b32_e32 v245, 7, v245
	v_lshl_add_u32 v244, v245, 16, v244
	s_mov_b32 m0, s3
	s_nop 0
	global_load_lds_dword v244, s[48:49]
	v_pk_add_f32 v[142:143], v[70:71], v[218:219]
	v_pk_add_f32 v[146:147], v[68:69], v[216:217]
	v_pk_add_f32 v[140:141], v[66:67], v[222:223]
	v_pk_add_f32 v[144:145], v[64:65], v[220:221]
	s_cbranch_scc0 .LBB0_345
	v_mul_f32_e32 v158, 0xbfb8aa3b, v144
	v_exp_f32_e32 v158, v158
	v_mul_f32_e32 v159, 0xbfb8aa3b, v147
	v_exp_f32_e32 v159, v159
	v_mul_f32_e32 v160, 0xbfb8aa3b, v145
	v_exp_f32_e32 v160, v160
	v_add_f32_e32 v158, 1.0, v158
	v_rcp_f32_e32 v179, v158
	v_add_f32_e32 v158, 1.0, v159
	v_mul_f32_e32 v159, 0xbfb8aa3b, v142
	v_rcp_f32_e32 v180, v158
	v_add_f32_e32 v158, 1.0, v160
	v_exp_f32_e32 v159, v159
	v_mul_f32_e32 v160, 0xbfb8aa3b, v140
	v_exp_f32_e32 v160, v160
	v_rcp_f32_e32 v181, v158
	v_add_f32_e32 v158, 1.0, v159
	v_mul_f32_e32 v159, 0xbfb8aa3b, v143
	v_mul_f32_e32 v156, 0xbfb8aa3b, v146
	v_rcp_f32_e32 v207, v158
	v_add_f32_e32 v158, 1.0, v160
	v_exp_f32_e32 v159, v159
	v_mul_f32_e32 v160, 0xbfb8aa3b, v141
	v_exp_f32_e32 v156, v156
	v_exp_f32_e32 v160, v160
	v_rcp_f32_e32 v208, v158
	v_add_f32_e32 v158, 1.0, v159
	v_add_f32_e32 v156, 1.0, v156
	v_rcp_f32_e32 v210, v158
	v_add_f32_e32 v158, 1.0, v160
	v_rcp_f32_e32 v156, v156
	v_rcp_f32_e32 v209, v158
	s_mov_b64 s[8:9], 0

.LBB0_393:
	s_andn2_b64 vcc, exec, s[8:9]
	s_cbranch_vccnz .LBB0_395
	v_ashrrev_i32_e32 v179, 31, v178
	v_lshlrev_b64 v[128:129], 12, v[178:179]
	v_lshl_add_u64 v[128:129], s[4:5], 0, v[128:129]
	s_mov_b32 s51, s29
	v_lshl_add_u64 v[128:129], v[128:129], 0, s[50:51]
	s_lshl_b32 s28, s23, 1
	v_lshl_add_u64 v[128:129], v[128:129], 0, s[28:29]
	v_lshlrev_b32_e32 v156, 1, v166
	v_lshl_add_u64 v[180:181], v[128:129], 0, v[156:157]
	global_load_dwordx4 v[128:131], v[176:177], off offset:16
	global_load_dwordx4 v[140:143], v[176:177], off
	global_load_dwordx4 v[132:135], v[176:177], off offset:528
	global_load_dwordx4 v[136:139], v[176:177], off offset:512
	s_mov_b32 s8, 0x9bff000
	s_waitcnt vmcnt(0)
	v_lshrrev_b32_e32 v244, 4, v167
	v_and_b32_e32 v245, 15, v167
	v_lshlrev_b32_e32 v244, 11, v244
	v_lshl_or_b32 v244, v245, 7, v244
	v_mov_b32_e32 v245, s44
	v_and_b32_e32 v245, 7, v245
	v_lshl_add_u32 v244, v245, 16, v244
	s_mov_b32 m0, s3
	s_nop 0
	global_load_lds_dword v244, s[48:49]
	v_pk_add_f32 v[160:161], v[120:121], v[128:129]
	v_pk_add_f32 v[144:145], v[124:125], v[140:141]
	v_pk_add_f32 v[146:147], v[126:127], v[142:143]
	v_pk_add_f32 v[208:209], v[68:69], v[136:137]
	v_mul_f32_e32 v144, 0xbfb8aa3b, v144
	v_exp_f32_e32 v214, v144
	v_mul_f32_e32 v144, 0xbfb8aa3b, v208
	v_exp_f32_e32 v215, v144
	v_pk_add_f32 v[192:193], v[70:71], v[138:139]
	v_pk_add_f32 v[212:213], v[64:65], v[132:133]
	v_pk_add_f32 v[158:159], v[122:123], v[130:131]
	v_pk_add_f32 v[214:215], v[214:215], 1.0 op_sel_hi:[1,0]
	v_pk_add_f32 v[210:211], v[66:67], v[134:135]
	v_mul_f32_e32 v144, v214, v215
	v_rcp_f32_e32 v144, v144
	s_nop 0
	v_mul_f32_e32 v156, v208, v144
	v_mul_f32_e32 v144, 0xbfb8aa3b, v145
	v_mul_f32_e32 v145, 0xbfb8aa3b, v209
	v_exp_f32_e32 v144, v144
	v_exp_f32_e32 v145, v145
	s_nop 0
	v_pk_add_f32 v[144:145], v[144:145], 1.0 op_sel_hi:[1,0]
	s_nop 0
	v_mul_f32_e32 v144, v144, v145
	v_rcp_f32_e32 v144, v144
	v_mul_f32_e32 v145, 0xbfb8aa3b, v146
	v_exp_f32_e32 v208, v145
	v_mul_f32_e32 v145, 0xbfb8aa3b, v192
	v_mul_f32_e32 v146, 0xbfb8aa3b, v147
	v_mul_f32_e32 v147, 0xbfb8aa3b, v193
	v_mul_f32_e32 v144, v209, v144
	v_exp_f32_e32 v209, v145
	v_exp_f32_e32 v146, v146
	v_exp_f32_e32 v147, v147
	v_cvt_pk_bf16_f32 v144, v156, v144
	v_pk_add_f32 v[208:209], v[208:209], 1.0 op_sel_hi:[1,0]
	v_pk_add_f32 v[146:147], v[146:147], 1.0 op_sel_hi:[1,0]
	v_mul_f32_e32 v145, v208, v209
	v_mul_f32_e32 v146, v146, v147
	v_rcp_f32_e32 v145, v145
	v_rcp_f32_e32 v146, v146
	v_mul_f32_e32 v147, 0xbfb8aa3b, v212
	v_exp_f32_e32 v147, v147
	v_mul_f32_e32 v145, v192, v145
	v_mul_f32_e32 v146, v193, v146
	v_cvt_pk_bf16_f32 v145, v145, v146
	v_mul_f32_e32 v146, 0xbfb8aa3b, v160
	v_exp_f32_e32 v146, v146
	v_pk_add_f32 v[208:209], v[52:53], v[136:137]
	v_pk_add_f32 v[192:193], v[54:55], v[138:139]
	v_pk_add_f32 v[146:147], v[146:147], 1.0 op_sel_hi:[1,0]
	s_nop 0
	v_mul_f32_e32 v146, v146, v147
	v_rcp_f32_e32 v146, v146
	v_mul_f32_e32 v147, 0xbfb8aa3b, v213
	v_exp_f32_e32 v147, v147
	v_mul_f32_e32 v156, v212, v146
	v_mul_f32_e32 v146, 0xbfb8aa3b, v161
	v_exp_f32_e32 v146, v146
	s_nop 0
	v_pk_add_f32 v[146:147], v[146:147], 1.0 op_sel_hi:[1,0]
	s_nop 0
	v_mul_f32_e32 v146, v146, v147
	v_rcp_f32_e32 v146, v146
	v_mul_f32_e32 v147, 0xbfb8aa3b, v158
	v_exp_f32_e32 v160, v147
	v_mul_f32_e32 v147, 0xbfb8aa3b, v210
	v_mul_f32_e32 v146, v213, v146
	v_cvt_pk_bf16_f32 v146, v156, v146
	v_mul_f32_e32 v156, 0xbfb8aa3b, v159
	v_exp_f32_e32 v161, v147
	v_exp_f32_e32 v158, v156
	v_mul_f32_e32 v156, 0xbfb8aa3b, v211
	v_exp_f32_e32 v159, v156
	v_pk_add_f32 v[160:161], v[160:161], 1.0 op_sel_hi:[1,0]
	v_pk_add_f32 v[212:213], v[50:51], v[134:135]
	v_mul_f32_e32 v147, v160, v161
	v_pk_add_f32 v[158:159], v[158:159], 1.0 op_sel_hi:[1,0]
	v_rcp_f32_e32 v147, v147
	v_mul_f32_e32 v156, v158, v159
	v_rcp_f32_e32 v156, v156
	v_add_co_u32_e32 v158, vcc, s8, v180
	v_mul_f32_e32 v147, v210, v147
	v_mul_f32_e32 v156, v211, v156
	v_cvt_pk_bf16_f32 v147, v147, v156
	v_addc_co_u32_e32 v159, vcc, 0, v181, vcc
	global_store_dwordx4 v[158:159], v[144:147], off
	v_pk_add_f32 v[160:161], v[112:113], v[128:129]
	v_pk_add_f32 v[210:211], v[48:49], v[132:133]
	v_pk_add_f32 v[146:147], v[116:117], v[140:141]
	v_pk_add_f32 v[144:145], v[118:119], v[142:143]
	v_mul_f32_e32 v146, 0xbfb8aa3b, v146
	v_exp_f32_e32 v214, v146
	v_mul_f32_e32 v146, 0xbfb8aa3b, v208
	v_exp_f32_e32 v215, v146
	v_mul_f32_e32 v144, 0xbfb8aa3b, v144
	v_pk_add_f32 v[158:159], v[114:115], v[130:131]
	s_mov_b32 s8, 0x9c0f000
	v_pk_add_f32 v[214:215], v[214:215], 1.0 op_sel_hi:[1,0]
	s_nop 0
	v_mul_f32_e32 v146, v214, v215
	v_rcp_f32_e32 v146, v146
	s_nop 0
	v_mul_f32_e32 v156, v208, v146
	v_mul_f32_e32 v146, 0xbfb8aa3b, v147
	v_mul_f32_e32 v147, 0xbfb8aa3b, v209
	v_exp_f32_e32 v146, v146
	v_exp_f32_e32 v147, v147
	s_nop 0
	v_pk_add_f32 v[146:147], v[146:147], 1.0 op_sel_hi:[1,0]
	s_nop 0
	v_mul_f32_e32 v146, v146, v147
	v_rcp_f32_e32 v146, v146
	s_nop 0
	v_mul_f32_e32 v146, v209, v146
	v_cvt_pk_bf16_f32 v208, v156, v146
	v_exp_f32_e32 v146, v144
	v_mul_f32_e32 v144, 0xbfb8aa3b, v192
	v_exp_f32_e32 v147, v144
	s_nop 0
	v_pk_add_f32 v[146:147], v[146:147], 1.0 op_sel_hi:[1,0]
	s_nop 0
	v_mul_f32_e32 v144, v146, v147
	v_rcp_f32_e32 v144, v144
	s_nop 0
	v_mul_f32_e32 v146, v192, v144
	v_mul_f32_e32 v144, 0xbfb8aa3b, v145
	v_mul_f32_e32 v145, 0xbfb8aa3b, v193
	v_exp_f32_e32 v144, v144
	v_exp_f32_e32 v145, v145
	s_nop 0
	v_pk_add_f32 v[144:145], v[144:145], 1.0 op_sel_hi:[1,0]
	s_nop 0
	v_mul_f32_e32 v144, v144, v145
	v_rcp_f32_e32 v144, v144
	v_mul_f32_e32 v145, 0xbfb8aa3b, v210
	v_exp_f32_e32 v145, v145
	v_mul_f32_e32 v144, v193, v144
	v_cvt_pk_bf16_f32 v209, v146, v144
	v_mul_f32_e32 v144, 0xbfb8aa3b, v160
	v_exp_f32_e32 v144, v144
	v_pk_add_f32 v[192:193], v[46:47], v[138:139]
	v_pk_add_f32 v[144:145], v[144:145], 1.0 op_sel_hi:[1,0]
	s_nop 0
	v_mul_f32_e32 v144, v144, v145
	v_rcp_f32_e32 v144, v144
	v_mul_f32_e32 v145, 0xbfb8aa3b, v211
	v_exp_f32_e32 v145, v145
	v_mul_f32_e32 v146, v210, v144
	v_mul_f32_e32 v144, 0xbfb8aa3b, v161
	v_exp_f32_e32 v144, v144
	v_pk_add_f32 v[160:161], v[104:105], v[128:129]
	v_pk_add_f32 v[144:145], v[144:145], 1.0 op_sel_hi:[1,0]
	s_nop 0
	v_mul_f32_e32 v144, v144, v145
	v_rcp_f32_e32 v144, v144
	v_mul_f32_e32 v145, 0xbfb8aa3b, v212
	v_exp_f32_e32 v145, v145
	v_mul_f32_e32 v144, v211, v144
	v_cvt_pk_bf16_f32 v210, v146, v144
	v_mul_f32_e32 v144, 0xbfb8aa3b, v158
	v_exp_f32_e32 v144, v144
	s_nop 0
	v_pk_add_f32 v[144:145], v[144:145], 1.0 op_sel_hi:[1,0]
	s_nop 0
	v_mul_f32_e32 v144, v144, v145
	v_rcp_f32_e32 v144, v144
	v_mul_f32_e32 v145, 0xbfb8aa3b, v213
	v_exp_f32_e32 v145, v145
	v_mul_f32_e32 v146, v212, v144
	v_mul_f32_e32 v144, 0xbfb8aa3b, v159
	v_exp_f32_e32 v144, v144
	v_pk_add_f32 v[158:159], v[106:107], v[130:131]
	v_pk_add_f32 v[144:145], v[144:145], 1.0 op_sel_hi:[1,0]
	s_nop 0
	v_mul_f32_e32 v144, v144, v145
	v_rcp_f32_e32 v144, v144
	s_nop 0
	v_mul_f32_e32 v144, v213, v144
	v_cvt_pk_bf16_f32 v211, v146, v144
	v_add_co_u32_e32 v144, vcc, s8, v180
	v_pk_add_f32 v[146:147], v[110:111], v[142:143]
	s_nop 0
	v_addc_co_u32_e32 v145, vcc, 0, v181, vcc
	global_store_dwordx4 v[144:145], v[208:211], off
	v_pk_add_f32 v[144:145], v[108:109], v[140:141]
	v_pk_add_f32 v[212:213], v[40:41], v[132:133]
	v_pk_add_f32 v[208:209], v[44:45], v[136:137]
	v_mul_f32_e32 v144, 0xbfb8aa3b, v144
	v_exp_f32_e32 v214, v144
	v_mul_f32_e32 v144, 0xbfb8aa3b, v208
	v_exp_f32_e32 v215, v144
	v_pk_add_f32 v[210:211], v[42:43], v[134:135]
	s_mov_b32 s8, 0x9c1f000
	v_pk_add_f32 v[214:215], v[214:215], 1.0 op_sel_hi:[1,0]
	s_nop 0
	v_mul_f32_e32 v144, v214, v215
	v_rcp_f32_e32 v144, v144
	s_nop 0
	v_mul_f32_e32 v156, v208, v144
	v_mul_f32_e32 v144, 0xbfb8aa3b, v145
	v_mul_f32_e32 v145, 0xbfb8aa3b, v209
	v_exp_f32_e32 v144, v144
	v_exp_f32_e32 v145, v145
	s_nop 0
	v_pk_add_f32 v[144:145], v[144:145], 1.0 op_sel_hi:[1,0]
	s_nop 0
	v_mul_f32_e32 v144, v144, v145
	v_rcp_f32_e32 v144, v144
	v_mul_f32_e32 v145, 0xbfb8aa3b, v146
	v_exp_f32_e32 v208, v145
	v_mul_f32_e32 v145, 0xbfb8aa3b, v192
	v_mul_f32_e32 v146, 0xbfb8aa3b, v147
	v_mul_f32_e32 v147, 0xbfb8aa3b, v193
	v_mul_f32_e32 v144, v209, v144
	v_exp_f32_e32 v209, v145
	v_exp_f32_e32 v146, v146
	v_exp_f32_e32 v147, v147
	v_cvt_pk_bf16_f32 v144, v156, v144
	v_pk_add_f32 v[208:209], v[208:209], 1.0 op_sel_hi:[1,0]
	v_pk_add_f32 v[146:147], v[146:147], 1.0 op_sel_hi:[1,0]
	v_mul_f32_e32 v145, v208, v209
	v_mul_f32_e32 v146, v146, v147
	v_rcp_f32_e32 v145, v145
	v_rcp_f32_e32 v146, v146
	v_mul_f32_e32 v147, 0xbfb8aa3b, v212
	v_exp_f32_e32 v147, v147
	v_mul_f32_e32 v145, v192, v145
	v_mul_f32_e32 v146, v193, v146
	v_cvt_pk_bf16_f32 v145, v145, v146
	v_mul_f32_e32 v146, 0xbfb8aa3b, v160
	v_exp_f32_e32 v146, v146
	v_pk_add_f32 v[208:209], v[36:37], v[136:137]
	v_pk_add_f32 v[192:193], v[38:39], v[138:139]
	v_pk_add_f32 v[146:147], v[146:147], 1.0 op_sel_hi:[1,0]
	s_nop 0
	v_mul_f32_e32 v146, v146, v147
	v_rcp_f32_e32 v146, v146
	v_mul_f32_e32 v147, 0xbfb8aa3b, v213
	v_exp_f32_e32 v147, v147
	v_mul_f32_e32 v156, v212, v146
	v_mul_f32_e32 v146, 0xbfb8aa3b, v161
	v_exp_f32_e32 v146, v146
	s_nop 0
	v_pk_add_f32 v[146:147], v[146:147], 1.0 op_sel_hi:[1,0]
	s_nop 0
	v_mul_f32_e32 v146, v146, v147
	v_rcp_f32_e32 v146, v146
	v_mul_f32_e32 v147, 0xbfb8aa3b, v158
	v_exp_f32_e32 v160, v147
	v_mul_f32_e32 v147, 0xbfb8aa3b, v210
	v_mul_f32_e32 v146, v213, v146
	v_cvt_pk_bf16_f32 v146, v156, v146
	v_mul_f32_e32 v156, 0xbfb8aa3b, v159
	v_exp_f32_e32 v161, v147
	v_exp_f32_e32 v158, v156
	v_mul_f32_e32 v156, 0xbfb8aa3b, v211
	v_exp_f32_e32 v159, v156
	v_pk_add_f32 v[160:161], v[160:161], 1.0 op_sel_hi:[1,0]
	v_pk_add_f32 v[212:213], v[32:33], v[132:133]
	v_mul_f32_e32 v147, v160, v161
	v_pk_add_f32 v[158:159], v[158:159], 1.0 op_sel_hi:[1,0]
	v_rcp_f32_e32 v147, v147
	v_mul_f32_e32 v156, v158, v159
	v_rcp_f32_e32 v156, v156
	v_add_co_u32_e32 v158, vcc, s8, v180
	v_mul_f32_e32 v147, v210, v147
	s_nop 0
	v_addc_co_u32_e32 v159, vcc, 0, v181, vcc
	v_mul_f32_e32 v156, v211, v156
	v_cvt_pk_bf16_f32 v147, v147, v156
	global_store_dwordx4 v[158:159], v[144:147], off
	v_pk_add_f32 v[160:161], v[96:97], v[128:129]
	v_pk_add_f32 v[158:159], v[98:99], v[130:131]
	v_pk_add_f32 v[144:145], v[100:101], v[140:141]
	v_pk_add_f32 v[146:147], v[102:103], v[142:143]
	v_mul_f32_e32 v144, 0xbfb8aa3b, v144
	v_exp_f32_e32 v214, v144
	v_mul_f32_e32 v144, 0xbfb8aa3b, v208
	v_exp_f32_e32 v215, v144
	v_pk_add_f32 v[210:211], v[34:35], v[134:135]
	s_mov_b32 s8, 0x9c2f000
	v_pk_add_f32 v[214:215], v[214:215], 1.0 op_sel_hi:[1,0]
	s_nop 0
	v_mul_f32_e32 v144, v214, v215
	v_rcp_f32_e32 v144, v144
	s_nop 0
	v_mul_f32_e32 v156, v208, v144
	v_mul_f32_e32 v144, 0xbfb8aa3b, v145
	v_mul_f32_e32 v145, 0xbfb8aa3b, v209
	v_exp_f32_e32 v144, v144
	v_exp_f32_e32 v145, v145
	s_nop 0
	v_pk_add_f32 v[144:145], v[144:145], 1.0 op_sel_hi:[1,0]
	s_nop 0
	v_mul_f32_e32 v144, v144, v145
	v_rcp_f32_e32 v144, v144
	v_mul_f32_e32 v145, 0xbfb8aa3b, v146
	v_exp_f32_e32 v208, v145
	v_mul_f32_e32 v145, 0xbfb8aa3b, v192
	v_mul_f32_e32 v146, 0xbfb8aa3b, v147
	v_mul_f32_e32 v147, 0xbfb8aa3b, v193
	v_mul_f32_e32 v144, v209, v144
	v_exp_f32_e32 v209, v145
	v_exp_f32_e32 v146, v146
	v_exp_f32_e32 v147, v147
	v_cvt_pk_bf16_f32 v144, v156, v144
	v_pk_add_f32 v[208:209], v[208:209], 1.0 op_sel_hi:[1,0]
	v_pk_add_f32 v[146:147], v[146:147], 1.0 op_sel_hi:[1,0]
	v_mul_f32_e32 v145, v208, v209
	v_mul_f32_e32 v146, v146, v147
	v_rcp_f32_e32 v145, v145
	v_rcp_f32_e32 v146, v146
	v_mul_f32_e32 v147, 0xbfb8aa3b, v212
	v_exp_f32_e32 v147, v147
	v_mul_f32_e32 v145, v192, v145
	v_mul_f32_e32 v146, v193, v146
	v_cvt_pk_bf16_f32 v145, v145, v146
	v_mul_f32_e32 v146, 0xbfb8aa3b, v160
	v_exp_f32_e32 v146, v146
	v_pk_add_f32 v[208:209], v[28:29], v[136:137]
	v_pk_add_f32 v[192:193], v[30:31], v[138:139]
	v_pk_add_f32 v[146:147], v[146:147], 1.0 op_sel_hi:[1,0]
	s_nop 0
	v_mul_f32_e32 v146, v146, v147
	v_rcp_f32_e32 v146, v146
	v_mul_f32_e32 v147, 0xbfb8aa3b, v213
	v_exp_f32_e32 v147, v147
	v_mul_f32_e32 v156, v212, v146
	v_mul_f32_e32 v146, 0xbfb8aa3b, v161
	v_exp_f32_e32 v146, v146
	s_nop 0
	v_pk_add_f32 v[146:147], v[146:147], 1.0 op_sel_hi:[1,0]
	s_nop 0
	v_mul_f32_e32 v146, v146, v147
	v_rcp_f32_e32 v146, v146
	v_mul_f32_e32 v147, 0xbfb8aa3b, v158
	v_exp_f32_e32 v160, v147
	v_mul_f32_e32 v147, 0xbfb8aa3b, v210
	v_mul_f32_e32 v146, v213, v146
	v_cvt_pk_bf16_f32 v146, v156, v146
	v_mul_f32_e32 v156, 0xbfb8aa3b, v159
	v_exp_f32_e32 v161, v147
	v_exp_f32_e32 v158, v156
	v_mul_f32_e32 v156, 0xbfb8aa3b, v211
	v_exp_f32_e32 v159, v156
	v_pk_add_f32 v[160:161], v[160:161], 1.0 op_sel_hi:[1,0]
	v_pk_add_f32 v[212:213], v[24:25], v[132:133]
	v_mul_f32_e32 v147, v160, v161
	v_pk_add_f32 v[158:159], v[158:159], 1.0 op_sel_hi:[1,0]
	v_rcp_f32_e32 v147, v147
	v_mul_f32_e32 v156, v158, v159
	v_rcp_f32_e32 v156, v156
	v_add_co_u32_e32 v158, vcc, s8, v180
	v_mul_f32_e32 v147, v210, v147
	s_nop 0
	v_addc_co_u32_e32 v159, vcc, 0, v181, vcc
	v_mul_f32_e32 v156, v211, v156
	v_cvt_pk_bf16_f32 v147, v147, v156
	global_store_dwordx4 v[158:159], v[144:147], off
	v_pk_add_f32 v[160:161], v[88:89], v[128:129]
	v_pk_add_f32 v[158:159], v[90:91], v[130:131]
	v_pk_add_f32 v[144:145], v[92:93], v[140:141]
	v_pk_add_f32 v[146:147], v[94:95], v[142:143]
	v_mul_f32_e32 v144, 0xbfb8aa3b, v144
	v_exp_f32_e32 v214, v144
	v_mul_f32_e32 v144, 0xbfb8aa3b, v208
	v_exp_f32_e32 v215, v144
	v_pk_add_f32 v[210:211], v[26:27], v[134:135]
	s_mov_b32 s8, 0x9c7f000
	v_pk_add_f32 v[214:215], v[214:215], 1.0 op_sel_hi:[1,0]
	s_nop 0
	v_mul_f32_e32 v144, v214, v215
	v_rcp_f32_e32 v144, v144
	s_nop 0
	v_mul_f32_e32 v156, v208, v144
	v_mul_f32_e32 v144, 0xbfb8aa3b, v145
	v_mul_f32_e32 v145, 0xbfb8aa3b, v209
	v_exp_f32_e32 v144, v144
	v_exp_f32_e32 v145, v145
	s_nop 0
	v_pk_add_f32 v[144:145], v[144:145], 1.0 op_sel_hi:[1,0]
	s_nop 0
	v_mul_f32_e32 v144, v144, v145
	v_rcp_f32_e32 v144, v144
	v_mul_f32_e32 v145, 0xbfb8aa3b, v146
	v_exp_f32_e32 v208, v145
	v_mul_f32_e32 v145, 0xbfb8aa3b, v192
	v_mul_f32_e32 v146, 0xbfb8aa3b, v147
	v_mul_f32_e32 v147, 0xbfb8aa3b, v193
	v_mul_f32_e32 v144, v209, v144
	v_exp_f32_e32 v209, v145
	v_exp_f32_e32 v146, v146
	v_exp_f32_e32 v147, v147
	v_cvt_pk_bf16_f32 v144, v156, v144
	v_pk_add_f32 v[208:209], v[208:209], 1.0 op_sel_hi:[1,0]
	v_pk_add_f32 v[146:147], v[146:147], 1.0 op_sel_hi:[1,0]
	v_mul_f32_e32 v145, v208, v209
	v_mul_f32_e32 v146, v146, v147
	v_rcp_f32_e32 v145, v145
	v_rcp_f32_e32 v146, v146
	v_mul_f32_e32 v147, 0xbfb8aa3b, v212
	v_exp_f32_e32 v147, v147
	v_mul_f32_e32 v145, v192, v145
	v_mul_f32_e32 v146, v193, v146
	v_cvt_pk_bf16_f32 v145, v145, v146
	v_mul_f32_e32 v146, 0xbfb8aa3b, v160
	v_exp_f32_e32 v146, v146
	v_pk_add_f32 v[208:209], v[20:21], v[136:137]
	v_pk_add_f32 v[192:193], v[22:23], v[138:139]
	v_pk_add_f32 v[146:147], v[146:147], 1.0 op_sel_hi:[1,0]
	s_nop 0
	v_mul_f32_e32 v146, v146, v147
	v_rcp_f32_e32 v146, v146
	v_mul_f32_e32 v147, 0xbfb8aa3b, v213
	v_exp_f32_e32 v147, v147
	v_mul_f32_e32 v156, v212, v146
	v_mul_f32_e32 v146, 0xbfb8aa3b, v161
	v_exp_f32_e32 v146, v146
	s_nop 0
	v_pk_add_f32 v[146:147], v[146:147], 1.0 op_sel_hi:[1,0]
	s_nop 0
	v_mul_f32_e32 v146, v146, v147
	v_rcp_f32_e32 v146, v146
	v_mul_f32_e32 v147, 0xbfb8aa3b, v158
	v_exp_f32_e32 v160, v147
	v_mul_f32_e32 v147, 0xbfb8aa3b, v210
	v_mul_f32_e32 v146, v213, v146
	v_cvt_pk_bf16_f32 v146, v156, v146
	v_mul_f32_e32 v156, 0xbfb8aa3b, v159
	v_exp_f32_e32 v161, v147
	v_exp_f32_e32 v158, v156
	v_mul_f32_e32 v156, 0xbfb8aa3b, v211
	v_exp_f32_e32 v159, v156
	v_pk_add_f32 v[160:161], v[160:161], 1.0 op_sel_hi:[1,0]
	v_pk_add_f32 v[212:213], v[16:17], v[132:133]
	v_mul_f32_e32 v147, v160, v161
	v_pk_add_f32 v[158:159], v[158:159], 1.0 op_sel_hi:[1,0]
	v_rcp_f32_e32 v147, v147
	v_mul_f32_e32 v156, v158, v159
	v_rcp_f32_e32 v156, v156
	v_add_co_u32_e32 v158, vcc, s8, v180
	v_mul_f32_e32 v147, v210, v147
	s_nop 0
	v_addc_co_u32_e32 v159, vcc, 0, v181, vcc
	v_mul_f32_e32 v156, v211, v156
	v_cvt_pk_bf16_f32 v147, v147, v156
	global_store_dwordx4 v[158:159], v[144:147], off
	v_pk_add_f32 v[160:161], v[80:81], v[128:129]
	v_pk_add_f32 v[158:159], v[82:83], v[130:131]
	v_pk_add_f32 v[144:145], v[84:85], v[140:141]
	v_pk_add_f32 v[146:147], v[86:87], v[142:143]
	v_mul_f32_e32 v144, 0xbfb8aa3b, v144
	v_exp_f32_e32 v214, v144
	v_mul_f32_e32 v144, 0xbfb8aa3b, v208
	v_exp_f32_e32 v215, v144
	v_pk_add_f32 v[210:211], v[18:19], v[134:135]
	s_mov_b32 s8, 0x9c8f000
	v_pk_add_f32 v[214:215], v[214:215], 1.0 op_sel_hi:[1,0]
	s_nop 0
	v_mul_f32_e32 v144, v214, v215
	v_rcp_f32_e32 v144, v144
	s_nop 0
	v_mul_f32_e32 v156, v208, v144
	v_mul_f32_e32 v144, 0xbfb8aa3b, v145
	v_mul_f32_e32 v145, 0xbfb8aa3b, v209
	v_exp_f32_e32 v144, v144
	v_exp_f32_e32 v145, v145
	s_nop 0
	v_pk_add_f32 v[144:145], v[144:145], 1.0 op_sel_hi:[1,0]
	s_nop 0
	v_mul_f32_e32 v144, v144, v145
	v_rcp_f32_e32 v144, v144
	v_mul_f32_e32 v145, 0xbfb8aa3b, v146
	v_exp_f32_e32 v208, v145
	v_mul_f32_e32 v145, 0xbfb8aa3b, v192
	v_mul_f32_e32 v146, 0xbfb8aa3b, v147
	v_mul_f32_e32 v147, 0xbfb8aa3b, v193
	v_mul_f32_e32 v144, v209, v144
	v_exp_f32_e32 v209, v145
	v_exp_f32_e32 v146, v146
	v_exp_f32_e32 v147, v147
	v_cvt_pk_bf16_f32 v144, v156, v144
	v_pk_add_f32 v[208:209], v[208:209], 1.0 op_sel_hi:[1,0]
	v_pk_add_f32 v[146:147], v[146:147], 1.0 op_sel_hi:[1,0]
	v_mul_f32_e32 v145, v208, v209
	v_mul_f32_e32 v146, v146, v147
	v_rcp_f32_e32 v145, v145
	v_rcp_f32_e32 v146, v146
	v_mul_f32_e32 v147, 0xbfb8aa3b, v212
	v_exp_f32_e32 v147, v147
	v_mul_f32_e32 v145, v192, v145
	v_mul_f32_e32 v146, v193, v146
	v_cvt_pk_bf16_f32 v145, v145, v146
	v_mul_f32_e32 v146, 0xbfb8aa3b, v160
	v_exp_f32_e32 v146, v146
	v_pk_add_f32 v[208:209], v[12:13], v[136:137]
	v_pk_add_f32 v[192:193], v[14:15], v[138:139]
	v_pk_add_f32 v[138:139], v[6:7], v[138:139]
	v_pk_add_f32 v[146:147], v[146:147], 1.0 op_sel_hi:[1,0]
	s_nop 0
	v_mul_f32_e32 v146, v146, v147
	v_rcp_f32_e32 v146, v146
	v_mul_f32_e32 v147, 0xbfb8aa3b, v213
	v_exp_f32_e32 v147, v147
	v_mul_f32_e32 v156, v212, v146
	v_mul_f32_e32 v146, 0xbfb8aa3b, v161
	v_exp_f32_e32 v146, v146
	s_nop 0
	v_pk_add_f32 v[146:147], v[146:147], 1.0 op_sel_hi:[1,0]
	s_nop 0
	v_mul_f32_e32 v146, v146, v147
	v_rcp_f32_e32 v146, v146
	v_mul_f32_e32 v147, 0xbfb8aa3b, v158
	v_exp_f32_e32 v160, v147
	v_mul_f32_e32 v147, 0xbfb8aa3b, v210
	v_mul_f32_e32 v146, v213, v146
	v_cvt_pk_bf16_f32 v146, v156, v146
	v_mul_f32_e32 v156, 0xbfb8aa3b, v159
	v_exp_f32_e32 v161, v147
	v_exp_f32_e32 v158, v156
	v_mul_f32_e32 v156, 0xbfb8aa3b, v211
	v_exp_f32_e32 v159, v156
	v_pk_add_f32 v[160:161], v[160:161], 1.0 op_sel_hi:[1,0]
	v_pk_add_f32 v[212:213], v[8:9], v[132:133]
	v_mul_f32_e32 v147, v160, v161
	v_pk_add_f32 v[158:159], v[158:159], 1.0 op_sel_hi:[1,0]
	v_rcp_f32_e32 v147, v147
	v_mul_f32_e32 v156, v158, v159
	v_rcp_f32_e32 v156, v156
	v_add_co_u32_e32 v158, vcc, s8, v180
	v_mul_f32_e32 v147, v210, v147
	s_nop 0
	v_addc_co_u32_e32 v159, vcc, 0, v181, vcc
	v_mul_f32_e32 v156, v211, v156
	v_cvt_pk_bf16_f32 v147, v147, v156
	global_store_dwordx4 v[158:159], v[144:147], off
	v_pk_add_f32 v[160:161], v[72:73], v[128:129]
	v_pk_add_f32 v[158:159], v[74:75], v[130:131]
	v_pk_add_f32 v[144:145], v[76:77], v[140:141]
	v_pk_add_f32 v[146:147], v[78:79], v[142:143]
	v_mul_f32_e32 v144, 0xbfb8aa3b, v144
	v_exp_f32_e32 v214, v144
	v_mul_f32_e32 v144, 0xbfb8aa3b, v208
	v_exp_f32_e32 v215, v144
	v_pk_add_f32 v[210:211], v[10:11], v[134:135]
	s_mov_b32 s8, 0x9c9f000
	v_pk_add_f32 v[140:141], v[60:61], v[140:141]
	v_pk_add_f32 v[214:215], v[214:215], 1.0 op_sel_hi:[1,0]
	v_pk_add_f32 v[142:143], v[62:63], v[142:143]
	v_mul_f32_e32 v144, v214, v215
	v_rcp_f32_e32 v144, v144
	v_pk_add_f32 v[132:133], v[0:1], v[132:133]
	v_pk_add_f32 v[134:135], v[2:3], v[134:135]
	v_mul_f32_e32 v156, v208, v144
	v_mul_f32_e32 v144, 0xbfb8aa3b, v145
	v_mul_f32_e32 v145, 0xbfb8aa3b, v209
	v_exp_f32_e32 v144, v144
	v_exp_f32_e32 v145, v145
	s_nop 0
	v_pk_add_f32 v[144:145], v[144:145], 1.0 op_sel_hi:[1,0]
	s_nop 0
	v_mul_f32_e32 v144, v144, v145
	v_rcp_f32_e32 v144, v144
	v_mul_f32_e32 v145, 0xbfb8aa3b, v146
	v_exp_f32_e32 v208, v145
	v_mul_f32_e32 v145, 0xbfb8aa3b, v192
	v_mul_f32_e32 v146, 0xbfb8aa3b, v147
	v_mul_f32_e32 v147, 0xbfb8aa3b, v193
	v_mul_f32_e32 v144, v209, v144
	v_exp_f32_e32 v209, v145
	v_exp_f32_e32 v146, v146
	v_exp_f32_e32 v147, v147
	v_cvt_pk_bf16_f32 v144, v156, v144
	v_pk_add_f32 v[208:209], v[208:209], 1.0 op_sel_hi:[1,0]
	v_pk_add_f32 v[146:147], v[146:147], 1.0 op_sel_hi:[1,0]
	v_mul_f32_e32 v145, v208, v209
	v_mul_f32_e32 v146, v146, v147
	v_rcp_f32_e32 v145, v145
	v_rcp_f32_e32 v146, v146
	v_mul_f32_e32 v147, 0xbfb8aa3b, v212
	v_exp_f32_e32 v147, v147
	v_mul_f32_e32 v145, v192, v145
	v_mul_f32_e32 v146, v193, v146
	v_cvt_pk_bf16_f32 v145, v145, v146
	v_mul_f32_e32 v146, 0xbfb8aa3b, v160
	v_exp_f32_e32 v146, v146
	s_nop 0
	v_pk_add_f32 v[146:147], v[146:147], 1.0 op_sel_hi:[1,0]
	s_nop 0
	v_mul_f32_e32 v146, v146, v147
	v_rcp_f32_e32 v146, v146
	v_mul_f32_e32 v147, 0xbfb8aa3b, v213
	v_exp_f32_e32 v147, v147
	v_mul_f32_e32 v156, v212, v146
	v_mul_f32_e32 v146, 0xbfb8aa3b, v161
	v_exp_f32_e32 v146, v146
	s_nop 0
	v_pk_add_f32 v[146:147], v[146:147], 1.0 op_sel_hi:[1,0]
	s_nop 0
	v_mul_f32_e32 v146, v146, v147
	v_rcp_f32_e32 v146, v146
	v_mul_f32_e32 v147, 0xbfb8aa3b, v158
	v_exp_f32_e32 v160, v147
	v_mul_f32_e32 v147, 0xbfb8aa3b, v210
	v_mul_f32_e32 v146, v213, v146
	v_cvt_pk_bf16_f32 v146, v156, v146
	v_mul_f32_e32 v156, 0xbfb8aa3b, v159
	v_exp_f32_e32 v161, v147
	v_exp_f32_e32 v158, v156
	v_mul_f32_e32 v156, 0xbfb8aa3b, v211
	v_exp_f32_e32 v159, v156
	v_pk_add_f32 v[160:161], v[160:161], 1.0 op_sel_hi:[1,0]
	v_pk_add_f32 v[158:159], v[158:159], 1.0 op_sel_hi:[1,0]
	v_mul_f32_e32 v147, v160, v161
	v_rcp_f32_e32 v147, v147
	v_mul_f32_e32 v156, v158, v159
	v_rcp_f32_e32 v156, v156
	v_add_co_u32_e32 v158, vcc, s8, v180
	v_mul_f32_e32 v147, v210, v147
	s_nop 0
	v_addc_co_u32_e32 v159, vcc, 0, v181, vcc
	v_mul_f32_e32 v156, v211, v156
	v_cvt_pk_bf16_f32 v147, v147, v156
	global_store_dwordx4 v[158:159], v[144:147], off
	s_nop 1
	v_pk_add_f32 v[144:145], v[58:59], v[130:131]
	v_pk_add_f32 v[130:131], v[56:57], v[128:129]
	v_pk_add_f32 v[128:129], v[4:5], v[136:137]
	v_mul_f32_e32 v136, 0xbfb8aa3b, v140
	v_mul_f32_e32 v137, 0xbfb8aa3b, v128
	v_exp_f32_e32 v136, v136
	v_exp_f32_e32 v137, v137
	v_mul_f32_e32 v130, 0xbfb8aa3b, v130
	v_pk_add_f32 v[136:137], v[136:137], 1.0 op_sel_hi:[1,0]
	s_nop 0
	v_mul_f32_e32 v136, v136, v137
	v_rcp_f32_e32 v136, v136
	v_mul_f32_e32 v137, 0xbfb8aa3b, v129
	v_exp_f32_e32 v137, v137
	v_mul_f32_e32 v128, v128, v136
	v_mul_f32_e32 v136, 0xbfb8aa3b, v141
	v_exp_f32_e32 v136, v136
	s_nop 0
	v_pk_add_f32 v[136:137], v[136:137], 1.0 op_sel_hi:[1,0]
	s_nop 0
	v_mul_f32_e32 v136, v136, v137
	v_rcp_f32_e32 v136, v136
	s_nop 0
	v_mul_f32_e32 v129, v129, v136
	v_cvt_pk_bf16_f32 v128, v128, v129
	v_mul_f32_e32 v129, 0xbfb8aa3b, v142
	v_exp_f32_e32 v136, v129
	v_mul_f32_e32 v129, 0xbfb8aa3b, v138
	v_exp_f32_e32 v137, v129
	s_nop 0
	v_pk_add_f32 v[136:137], v[136:137], 1.0 op_sel_hi:[1,0]
	s_nop 0
	v_mul_f32_e32 v129, v136, v137
	v_mul_f32_e32 v136, 0xbfb8aa3b, v143
	v_mul_f32_e32 v137, 0xbfb8aa3b, v139
	v_exp_f32_e32 v136, v136
	v_exp_f32_e32 v137, v137
	v_rcp_f32_e32 v129, v129
	v_pk_add_f32 v[136:137], v[136:137], 1.0 op_sel_hi:[1,0]
	s_nop 0
	v_mul_f32_e32 v136, v136, v137
	v_rcp_f32_e32 v136, v136
	v_mul_f32_e32 v129, v138, v129
	v_mul_f32_e32 v136, v139, v136
	v_cvt_pk_bf16_f32 v129, v129, v136
	v_exp_f32_e32 v136, v130
	v_mul_f32_e32 v130, 0xbfb8aa3b, v132
	v_exp_f32_e32 v137, v130
	s_nop 0
	v_pk_add_f32 v[136:137], v[136:137], 1.0 op_sel_hi:[1,0]
	s_nop 0
	v_mul_f32_e32 v130, v136, v137
	v_rcp_f32_e32 v130, v130
	s_nop 0
	v_mul_f32_e32 v132, v132, v130
	v_mul_f32_e32 v130, 0xbfb8aa3b, v131
	v_mul_f32_e32 v131, 0xbfb8aa3b, v133
	v_exp_f32_e32 v130, v130
	v_exp_f32_e32 v131, v131
	s_nop 0
	v_pk_add_f32 v[130:131], v[130:131], 1.0 op_sel_hi:[1,0]
	s_nop 0
	v_mul_f32_e32 v130, v130, v131
	v_rcp_f32_e32 v130, v130
	v_mul_f32_e32 v131, 0xbfb8aa3b, v144
	v_mul_f32_e32 v130, v133, v130
	v_cvt_pk_bf16_f32 v130, v132, v130
	v_exp_f32_e32 v132, v131
	v_mul_f32_e32 v131, 0xbfb8aa3b, v134
	v_exp_f32_e32 v133, v131
	s_nop 0
	v_pk_add_f32 v[132:133], v[132:133], 1.0 op_sel_hi:[1,0]
	s_nop 0
	v_mul_f32_e32 v131, v132, v133
	v_mul_f32_e32 v132, 0xbfb8aa3b, v145
	v_mul_f32_e32 v133, 0xbfb8aa3b, v135
	v_exp_f32_e32 v132, v132
	v_exp_f32_e32 v133, v133
	v_rcp_f32_e32 v131, v131
	v_pk_add_f32 v[132:133], v[132:133], 1.0 op_sel_hi:[1,0]
	s_nop 0
	v_mul_f32_e32 v132, v132, v133
	v_rcp_f32_e32 v132, v132
	v_mul_f32_e32 v131, v134, v131
	v_mul_f32_e32 v132, v135, v132
	v_cvt_pk_bf16_f32 v131, v131, v132
	v_add_co_u32_e32 v132, vcc, 0x9caf000, v180
	s_nop 1
	v_addc_co_u32_e32 v133, vcc, 0, v181, vcc
	global_store_dwordx4 v[132:133], v[128:131], off

.LBB0_396:
	s_nop 0
	v_add_u32_e32 v128, s50, v205
	v_mul_lo_u32 v156, v128, s68
	v_lshl_add_u64 v[128:129], v[156:157], 1, s[78:79]
	v_ashrrev_i32_e32 v179, 31, v178
	v_lshl_add_u64 v[136:137], v[178:179], 1, v[128:129]
	global_load_dwordx4 v[128:131], v[176:177], off offset:16
	global_load_dwordx4 v[132:135], v[176:177], off
	s_movk_i32 s8, 0x4000
	s_waitcnt vmcnt(0)
	v_pk_add_f32 v[138:139], v[120:121], v[128:129]
	v_pk_add_f32 v[124:125], v[124:125], v[132:133]
	v_pk_add_f32 v[142:143], v[122:123], v[130:131]
	v_cvt_pk_bf16_f32 v120, v124, v124
	global_store_short v[136:137], v120, off
	v_add_co_u32_e32 v120, vcc, s8, v136
	v_cvt_pk_bf16_f32 v122, v125, v125
	s_mov_b32 s8, 0x8000
	s_nop 0
	v_addc_co_u32_e32 v121, vcc, 0, v137, vcc
	global_store_short v[120:121], v122, off offset:128
	v_add_co_u32_e32 v122, vcc, s8, v136
	v_pk_add_f32 v[126:127], v[126:127], v[134:135]
	s_nop 0
	v_addc_co_u32_e32 v123, vcc, 0, v137, vcc
	v_cvt_pk_bf16_f32 v124, v126, v126
	s_mov_b32 s8, 0xc000
	global_store_short v[122:123], v124, off offset:256
	v_add_co_u32_e32 v124, vcc, s8, v136
	v_cvt_pk_bf16_f32 v126, v127, v127
	s_mov_b32 s8, 0x10000
	s_nop 0
	v_addc_co_u32_e32 v125, vcc, 0, v137, vcc
	global_store_short v[124:125], v126, off offset:384
	v_add_co_u32_e32 v126, vcc, s8, v136
	v_cvt_pk_bf16_f32 v138, v138, v138
	s_mov_b32 s8, 0x14000
	s_nop 0
	v_addc_co_u32_e32 v127, vcc, 0, v137, vcc
	global_store_short v[126:127], v138, off offset:512
	v_add_co_u32_e32 v138, vcc, s8, v136
	v_cvt_pk_bf16_f32 v140, v139, v139
	s_mov_b32 s8, 0x18000
	s_nop 0
	v_addc_co_u32_e32 v139, vcc, 0, v137, vcc
	global_store_short v[138:139], v140, off offset:640
	v_add_co_u32_e32 v140, vcc, s8, v136
	v_pk_add_f32 v[116:117], v[116:117], v[132:133]
	v_pk_add_f32 v[112:113], v[112:113], v[128:129]
	v_pk_add_f32 v[108:109], v[108:109], v[132:133]
	v_pk_add_f32 v[104:105], v[104:105], v[128:129]
	v_pk_add_f32 v[100:101], v[100:101], v[132:133]
	v_pk_add_f32 v[96:97], v[96:97], v[128:129]
	v_pk_add_f32 v[92:93], v[92:93], v[132:133]
	v_pk_add_f32 v[88:89], v[88:89], v[128:129]
	v_pk_add_f32 v[84:85], v[84:85], v[132:133]
	v_pk_add_f32 v[80:81], v[80:81], v[128:129]
	v_pk_add_f32 v[76:77], v[76:77], v[132:133]
	v_pk_add_f32 v[72:73], v[72:73], v[128:129]
	v_pk_add_f32 v[60:61], v[60:61], v[132:133]
	v_pk_add_f32 v[56:57], v[56:57], v[128:129]
	v_cvt_pk_bf16_f32 v142, v142, v142
	v_addc_co_u32_e32 v141, vcc, 0, v137, vcc
	s_mov_b32 s8, 0x1c000
	v_cvt_pk_bf16_f32 v116, v116, v116
	v_cvt_pk_bf16_f32 v112, v112, v112
	v_cvt_pk_bf16_f32 v108, v108, v108
	v_cvt_pk_bf16_f32 v104, v104, v104
	v_cvt_pk_bf16_f32 v100, v100, v100
	v_cvt_pk_bf16_f32 v96, v96, v96
	v_cvt_pk_bf16_f32 v92, v92, v92
	v_cvt_pk_bf16_f32 v88, v88, v88
	v_cvt_pk_bf16_f32 v84, v84, v84
	v_cvt_pk_bf16_f32 v80, v80, v80
	v_cvt_pk_bf16_f32 v76, v76, v76
	v_cvt_pk_bf16_f32 v72, v72, v72
	v_cvt_pk_bf16_f32 v60, v60, v60
	v_cvt_pk_bf16_f32 v56, v56, v56
	global_store_short v[140:141], v142, off offset:768
	v_add_co_u32_e32 v142, vcc, s8, v136
	global_store_short v[136:137], v116, off offset:32
	v_cvt_pk_bf16_f32 v116, v117, v117
	global_store_short v[126:127], v112, off offset:544
	v_cvt_pk_bf16_f32 v112, v113, v113
	global_store_short v[136:137], v108, off offset:64
	v_cvt_pk_bf16_f32 v108, v109, v109
	global_store_short v[126:127], v104, off offset:576
	v_cvt_pk_bf16_f32 v104, v105, v105
	global_store_short v[136:137], v100, off offset:96
	v_cvt_pk_bf16_f32 v100, v101, v101
	global_store_short v[126:127], v96, off offset:608
	v_cvt_pk_bf16_f32 v96, v97, v97
	global_store_short v[136:137], v92, off offset:256
	v_cvt_pk_bf16_f32 v92, v93, v93
	global_store_short v[126:127], v88, off offset:768
	v_cvt_pk_bf16_f32 v88, v89, v89
	global_store_short v[136:137], v84, off offset:288
	v_cvt_pk_bf16_f32 v84, v85, v85
	global_store_short v[126:127], v80, off offset:800
	v_cvt_pk_bf16_f32 v80, v81, v81
	global_store_short v[136:137], v76, off offset:320
	v_cvt_pk_bf16_f32 v76, v77, v77
	global_store_short v[126:127], v72, off offset:832
	v_cvt_pk_bf16_f32 v72, v73, v73
	global_store_short v[136:137], v60, off offset:352
	v_cvt_pk_bf16_f32 v60, v61, v61
	global_store_short v[126:127], v56, off offset:864
	v_cvt_pk_bf16_f32 v56, v57, v57
	v_cvt_pk_bf16_f32 v144, v143, v143
	v_addc_co_u32_e32 v143, vcc, 0, v137, vcc
	v_pk_add_f32 v[118:119], v[118:119], v[134:135]
	v_pk_add_f32 v[114:115], v[114:115], v[130:131]
	global_store_short v[120:121], v116, off offset:160
	v_cvt_pk_bf16_f32 v116, v118, v118
	global_store_short v[138:139], v112, off offset:672
	v_cvt_pk_bf16_f32 v112, v114, v114
	v_pk_add_f32 v[110:111], v[110:111], v[134:135]
	v_pk_add_f32 v[106:107], v[106:107], v[130:131]
	global_store_short v[120:121], v108, off offset:192
	v_cvt_pk_bf16_f32 v108, v110, v110
	global_store_short v[138:139], v104, off offset:704
	v_cvt_pk_bf16_f32 v104, v106, v106
	v_pk_add_f32 v[102:103], v[102:103], v[134:135]
	v_pk_add_f32 v[98:99], v[98:99], v[130:131]
	global_store_short v[120:121], v100, off offset:224
	v_cvt_pk_bf16_f32 v100, v102, v102
	global_store_short v[138:139], v96, off offset:736
	v_cvt_pk_bf16_f32 v96, v98, v98
	v_pk_add_f32 v[94:95], v[94:95], v[134:135]
	v_pk_add_f32 v[90:91], v[90:91], v[130:131]
	global_store_short v[120:121], v92, off offset:384
	v_cvt_pk_bf16_f32 v92, v94, v94
	global_store_short v[138:139], v88, off offset:896
	v_cvt_pk_bf16_f32 v88, v90, v90
	v_pk_add_f32 v[86:87], v[86:87], v[134:135]
	v_pk_add_f32 v[82:83], v[82:83], v[130:131]
	global_store_short v[120:121], v84, off offset:416
	v_cvt_pk_bf16_f32 v84, v86, v86
	global_store_short v[138:139], v80, off offset:928
	v_cvt_pk_bf16_f32 v80, v82, v82
	v_pk_add_f32 v[78:79], v[78:79], v[134:135]
	v_pk_add_f32 v[74:75], v[74:75], v[130:131]
	global_store_short v[120:121], v76, off offset:448
	v_cvt_pk_bf16_f32 v76, v78, v78
	global_store_short v[138:139], v72, off offset:960
	v_cvt_pk_bf16_f32 v72, v74, v74
	v_pk_add_f32 v[62:63], v[62:63], v[134:135]
	v_pk_add_f32 v[58:59], v[58:59], v[130:131]
	global_store_short v[120:121], v60, off offset:480
	v_cvt_pk_bf16_f32 v60, v62, v62
	global_store_short v[138:139], v56, off offset:992
	v_cvt_pk_bf16_f32 v56, v58, v58
	global_store_short v[142:143], v144, off offset:896
	global_store_short v[122:123], v116, off offset:288
	v_cvt_pk_bf16_f32 v116, v119, v119
	global_store_short v[124:125], v116, off offset:416
	global_store_short v[140:141], v112, off offset:800
	v_cvt_pk_bf16_f32 v112, v115, v115
	global_store_short v[142:143], v112, off offset:928
	global_store_short v[122:123], v108, off offset:320
	v_cvt_pk_bf16_f32 v108, v111, v111
	global_store_short v[124:125], v108, off offset:448
	global_store_short v[140:141], v104, off offset:832
	v_cvt_pk_bf16_f32 v104, v107, v107
	global_store_short v[142:143], v104, off offset:960
	global_store_short v[122:123], v100, off offset:352
	v_cvt_pk_bf16_f32 v100, v103, v103
	global_store_short v[124:125], v100, off offset:480
	global_store_short v[140:141], v96, off offset:864
	v_cvt_pk_bf16_f32 v96, v99, v99
	global_store_short v[142:143], v96, off offset:992
	global_store_short v[122:123], v92, off offset:512
	v_cvt_pk_bf16_f32 v92, v95, v95
	global_store_short v[124:125], v92, off offset:640
	global_store_short v[140:141], v88, off offset:1024
	v_cvt_pk_bf16_f32 v88, v91, v91
	global_store_short v[142:143], v88, off offset:1152
	global_store_short v[122:123], v84, off offset:544
	v_cvt_pk_bf16_f32 v84, v87, v87
	global_store_short v[124:125], v84, off offset:672
	global_store_short v[140:141], v80, off offset:1056
	v_cvt_pk_bf16_f32 v80, v83, v83
	global_store_short v[142:143], v80, off offset:1184
	global_store_short v[122:123], v76, off offset:576
	v_cvt_pk_bf16_f32 v76, v79, v79
	global_store_short v[124:125], v76, off offset:704
	global_store_short v[140:141], v72, off offset:1088
	v_cvt_pk_bf16_f32 v72, v75, v75
	global_store_short v[142:143], v72, off offset:1216
	global_store_short v[122:123], v60, off offset:608
	v_cvt_pk_bf16_f32 v60, v63, v63
	global_store_short v[124:125], v60, off offset:736
	global_store_short v[140:141], v56, off offset:1120
	v_cvt_pk_bf16_f32 v56, v59, v59
	global_store_short v[142:143], v56, off offset:1248
	global_load_dwordx4 v[56:59], v[176:177], off offset:528
	s_nop 0
	global_load_dwordx4 v[60:63], v[176:177], off offset:512
	s_mov_b32 s8, 0x204000
	s_waitcnt vmcnt(1)
	v_pk_add_f32 v[74:75], v[64:65], v[56:57]
	v_add_co_u32_e32 v64, vcc, s8, v136
	s_waitcnt vmcnt(0)
	v_lshrrev_b32_e32 v244, 4, v167
	v_and_b32_e32 v245, 15, v167
	v_lshlrev_b32_e32 v244, 11, v244
	v_lshl_or_b32 v244, v245, 7, v244
	v_mov_b32_e32 v245, s44
	v_and_b32_e32 v245, 7, v245
	v_lshl_add_u32 v244, v245, 16, v244
	s_mov_b32 m0, s3
	s_nop 0
	global_load_lds_dword v244, s[48:49]
	v_pk_add_f32 v[68:69], v[68:69], v[60:61]
	v_pk_add_f32 v[72:73], v[66:67], v[58:59]
	v_cvt_pk_bf16_f32 v66, v68, v68
	v_addc_co_u32_e32 v65, vcc, 0, v137, vcc
	s_mov_b32 s8, 0x208000
	global_store_short v[64:65], v66, off
	v_add_co_u32_e32 v66, vcc, s8, v136
	v_cvt_pk_bf16_f32 v68, v69, v69
	s_mov_b32 s8, 0x20c000
	s_nop 0
	v_addc_co_u32_e32 v67, vcc, 0, v137, vcc
	v_pk_add_f32 v[70:71], v[70:71], v[62:63]
	global_store_short v[66:67], v68, off offset:128
	v_add_co_u32_e32 v68, vcc, s8, v136
	v_cvt_pk_bf16_f32 v70, v70, v70
	s_mov_b32 s8, 0x210000
	s_nop 0
	v_addc_co_u32_e32 v69, vcc, 0, v137, vcc
	global_store_short v[68:69], v70, off offset:256
	v_add_co_u32_e32 v70, vcc, s8, v136
	v_cvt_pk_bf16_f32 v76, v71, v71
	s_mov_b32 s8, 0x214000
	s_nop 0
	v_addc_co_u32_e32 v71, vcc, 0, v137, vcc
	global_store_short v[70:71], v76, off offset:384
	v_add_co_u32_e32 v76, vcc, s8, v136
	v_cvt_pk_bf16_f32 v74, v74, v74
	s_mov_b32 s8, 0x218000
	s_nop 0
	v_addc_co_u32_e32 v77, vcc, 0, v137, vcc
	global_store_short v[76:77], v74, off offset:512
	v_add_co_u32_e32 v74, vcc, s8, v136
	v_cvt_pk_bf16_f32 v78, v75, v75
	s_mov_b32 s8, 0x21c000
	s_nop 0
	v_addc_co_u32_e32 v75, vcc, 0, v137, vcc
	global_store_short v[74:75], v78, off offset:640
	v_add_co_u32_e32 v78, vcc, s8, v136
	v_pk_add_f32 v[52:53], v[52:53], v[60:61]
	v_pk_add_f32 v[48:49], v[48:49], v[56:57]
	v_pk_add_f32 v[44:45], v[44:45], v[60:61]
	v_pk_add_f32 v[40:41], v[40:41], v[56:57]
	v_pk_add_f32 v[36:37], v[36:37], v[60:61]
	v_pk_add_f32 v[32:33], v[32:33], v[56:57]
	v_pk_add_f32 v[28:29], v[28:29], v[60:61]
	v_pk_add_f32 v[24:25], v[24:25], v[56:57]
	v_pk_add_f32 v[20:21], v[20:21], v[60:61]
	v_pk_add_f32 v[16:17], v[16:17], v[56:57]
	v_pk_add_f32 v[12:13], v[12:13], v[60:61]
	v_pk_add_f32 v[8:9], v[8:9], v[56:57]
	v_pk_add_f32 v[4:5], v[4:5], v[60:61]
	v_pk_add_f32 v[0:1], v[0:1], v[56:57]
	v_cvt_pk_bf16_f32 v72, v72, v72
	v_addc_co_u32_e32 v79, vcc, 0, v137, vcc
	s_mov_b32 s8, 0x220000
	v_cvt_pk_bf16_f32 v52, v52, v52
	v_cvt_pk_bf16_f32 v48, v48, v48
	v_cvt_pk_bf16_f32 v44, v44, v44
	v_cvt_pk_bf16_f32 v40, v40, v40
	v_cvt_pk_bf16_f32 v36, v36, v36
	v_cvt_pk_bf16_f32 v32, v32, v32
	v_cvt_pk_bf16_f32 v28, v28, v28
	v_cvt_pk_bf16_f32 v24, v24, v24
	v_cvt_pk_bf16_f32 v20, v20, v20
	v_cvt_pk_bf16_f32 v16, v16, v16
	v_cvt_pk_bf16_f32 v12, v12, v12
	v_cvt_pk_bf16_f32 v8, v8, v8
	v_cvt_pk_bf16_f32 v4, v4, v4
	v_cvt_pk_bf16_f32 v0, v0, v0
	global_store_short v[78:79], v72, off offset:768
	v_add_co_u32_e32 v72, vcc, s8, v136
	global_store_short v[64:65], v52, off offset:32
	v_cvt_pk_bf16_f32 v52, v53, v53
	global_store_short v[76:77], v48, off offset:544
	v_cvt_pk_bf16_f32 v48, v49, v49
	global_store_short v[64:65], v44, off offset:64
	v_cvt_pk_bf16_f32 v44, v45, v45
	global_store_short v[76:77], v40, off offset:576
	v_cvt_pk_bf16_f32 v40, v41, v41
	global_store_short v[64:65], v36, off offset:96
	v_cvt_pk_bf16_f32 v36, v37, v37
	global_store_short v[76:77], v32, off offset:608
	v_cvt_pk_bf16_f32 v32, v33, v33
	global_store_short v[64:65], v28, off offset:256
	v_cvt_pk_bf16_f32 v28, v29, v29
	global_store_short v[76:77], v24, off offset:768
	v_cvt_pk_bf16_f32 v24, v25, v25
	global_store_short v[64:65], v20, off offset:288
	v_cvt_pk_bf16_f32 v20, v21, v21
	global_store_short v[76:77], v16, off offset:800
	v_cvt_pk_bf16_f32 v16, v17, v17
	global_store_short v[64:65], v12, off offset:320
	v_cvt_pk_bf16_f32 v12, v13, v13
	global_store_short v[76:77], v8, off offset:832
	v_cvt_pk_bf16_f32 v8, v9, v9
	global_store_short v[64:65], v4, off offset:352
	v_cvt_pk_bf16_f32 v4, v5, v5
	global_store_short v[76:77], v0, off offset:864
	v_cvt_pk_bf16_f32 v0, v1, v1
	v_cvt_pk_bf16_f32 v80, v73, v73
	v_addc_co_u32_e32 v73, vcc, 0, v137, vcc
	v_pk_add_f32 v[54:55], v[54:55], v[62:63]
	v_pk_add_f32 v[50:51], v[50:51], v[58:59]
	global_store_short v[66:67], v52, off offset:160
	v_cvt_pk_bf16_f32 v52, v54, v54
	global_store_short v[74:75], v48, off offset:672
	v_cvt_pk_bf16_f32 v48, v50, v50
	v_pk_add_f32 v[46:47], v[46:47], v[62:63]
	v_pk_add_f32 v[42:43], v[42:43], v[58:59]
	global_store_short v[66:67], v44, off offset:192
	v_cvt_pk_bf16_f32 v44, v46, v46
	global_store_short v[74:75], v40, off offset:704
	v_cvt_pk_bf16_f32 v40, v42, v42
	v_pk_add_f32 v[38:39], v[38:39], v[62:63]
	v_pk_add_f32 v[34:35], v[34:35], v[58:59]
	global_store_short v[66:67], v36, off offset:224
	v_cvt_pk_bf16_f32 v36, v38, v38
	global_store_short v[74:75], v32, off offset:736
	v_cvt_pk_bf16_f32 v32, v34, v34
	v_pk_add_f32 v[30:31], v[30:31], v[62:63]
	v_pk_add_f32 v[26:27], v[26:27], v[58:59]
	global_store_short v[66:67], v28, off offset:384
	v_cvt_pk_bf16_f32 v28, v30, v30
	global_store_short v[74:75], v24, off offset:896
	v_cvt_pk_bf16_f32 v24, v26, v26
	v_pk_add_f32 v[22:23], v[22:23], v[62:63]
	v_pk_add_f32 v[18:19], v[18:19], v[58:59]
	global_store_short v[66:67], v20, off offset:416
	v_cvt_pk_bf16_f32 v20, v22, v22
	global_store_short v[74:75], v16, off offset:928
	v_cvt_pk_bf16_f32 v16, v18, v18
	v_pk_add_f32 v[14:15], v[14:15], v[62:63]
	v_pk_add_f32 v[10:11], v[10:11], v[58:59]
	global_store_short v[66:67], v12, off offset:448
	v_cvt_pk_bf16_f32 v12, v14, v14
	global_store_short v[74:75], v8, off offset:960
	v_cvt_pk_bf16_f32 v8, v10, v10
	v_pk_add_f32 v[6:7], v[6:7], v[62:63]
	v_pk_add_f32 v[2:3], v[2:3], v[58:59]
	global_store_short v[66:67], v4, off offset:480
	v_cvt_pk_bf16_f32 v4, v6, v6
	global_store_short v[74:75], v0, off offset:992
	v_cvt_pk_bf16_f32 v0, v2, v2
	global_store_short v[72:73], v80, off offset:896
	global_store_short v[68:69], v52, off offset:288
	v_cvt_pk_bf16_f32 v52, v55, v55
	global_store_short v[70:71], v52, off offset:416
	global_store_short v[78:79], v48, off offset:800
	v_cvt_pk_bf16_f32 v48, v51, v51
	global_store_short v[72:73], v48, off offset:928
	global_store_short v[68:69], v44, off offset:320
	v_cvt_pk_bf16_f32 v44, v47, v47
	global_store_short v[70:71], v44, off offset:448
	global_store_short v[78:79], v40, off offset:832
	v_cvt_pk_bf16_f32 v40, v43, v43
	global_store_short v[72:73], v40, off offset:960
	global_store_short v[68:69], v36, off offset:352
	v_cvt_pk_bf16_f32 v36, v39, v39
	global_store_short v[70:71], v36, off offset:480
	global_store_short v[78:79], v32, off offset:864
	v_cvt_pk_bf16_f32 v32, v35, v35
	global_store_short v[72:73], v32, off offset:992
	global_store_short v[68:69], v28, off offset:512
	v_cvt_pk_bf16_f32 v28, v31, v31
	global_store_short v[70:71], v28, off offset:640
	global_store_short v[78:79], v24, off offset:1024
	v_cvt_pk_bf16_f32 v24, v27, v27
	global_store_short v[72:73], v24, off offset:1152
	global_store_short v[68:69], v20, off offset:544
	v_cvt_pk_bf16_f32 v20, v23, v23
	global_store_short v[70:71], v20, off offset:672
	global_store_short v[78:79], v16, off offset:1056
	v_cvt_pk_bf16_f32 v16, v19, v19
	global_store_short v[72:73], v16, off offset:1184
	global_store_short v[68:69], v12, off offset:576
	v_cvt_pk_bf16_f32 v12, v15, v15
	global_store_short v[70:71], v12, off offset:704
	global_store_short v[78:79], v8, off offset:1088
	v_cvt_pk_bf16_f32 v8, v11, v11
	global_store_short v[72:73], v8, off offset:1216
	global_store_short v[68:69], v4, off offset:608
	v_cvt_pk_bf16_f32 v4, v7, v7
	global_store_short v[70:71], v4, off offset:736
	global_store_short v[78:79], v0, off offset:1120
	v_cvt_pk_bf16_f32 v0, v3, v3
	global_store_short v[72:73], v0, off offset:1248
	s_andn2_b64 vcc, exec, s[38:39]
	s_mov_b64 s[8:9], -1
	s_cbranch_vccnz .LBB0_273
